# no s_setprio toggles; one static s_setprio 1 for waves 0-3 at kernel entry
# baseline (speedup 1.0000x reference)
_Z10fwd_kernel4Args:
	s_load_dwordx4 s[84:87], s[0:1], 0xd8
	s_load_dwordx2 s[64:65], s[0:1], 0x108
	s_load_dwordx8 s[68:75], s[0:1], 0xe8
	v_and_b32_e32 v188, 0x3ff, v0
	s_mov_b32 s94, s2
	s_mov_b64 s[90:91], s[0:1]
	v_readfirstlane_b32 s92, v188
	s_cmpk_ge_u32 s92, 0x100
	s_cbranch_scc1 .Lprio_skip
	s_setprio 1
.Lprio_skip:
	v_cmp_gt_u32_e32 vcc, 16, v188
	s_and_saveexec_b64 s[0:1], vcc
	v_lshl_add_u32 v1, v188, 2, 0
	v_add_u32_e32 v1, 0x23fc0, v1
	v_mov_b32_e32 v2, 0
	ds_write_b32 v1, v2
	s_or_b64 exec, exec, s[0:1]
	s_waitcnt lgkmcnt(0)
	s_add_u32 s0, s86, 0x1000
	s_addc_u32 s1, s87, 0
	v_writelane_b32 v240, s0, 0
	s_barrier
	s_nop 0
	v_writelane_b32 v240, s1, 1
	s_getreg_b32 s0, hwreg(HW_REG_XCC_ID, 0, 4)
	s_and_b32 s0, s0, 15
	v_writelane_b32 v240, s0, 2
	v_cmp_eq_u32_e64 s[2:3], 0, v188
	s_mov_b64 s[0:1], exec
	s_nop 0
	v_writelane_b32 v240, s2, 3
	s_nop 1
	v_writelane_b32 v240, s3, 4
	s_and_b64 s[2:3], s[0:1], s[2:3]
	s_mov_b64 exec, s[2:3]
	s_cbranch_execz .LBB0_5
	s_mov_b64 s[4:5], exec
	v_mbcnt_lo_u32_b32 v1, s4, 0
	v_mbcnt_hi_u32_b32 v1, s5, v1
	v_cmp_eq_u32_e32 vcc, 0, v1
	s_and_b64 s[2:3], exec, vcc
	s_mov_b64 exec, s[2:3]
	s_cbranch_execz .LBB0_5
	v_readlane_b32 s2, v240, 2
	s_lshl_b32 s2, s2, 8
	s_bcnt1_i32_b64 s3, s[4:5]
	v_mov_b32_e32 v1, s2
	v_mov_b32_e32 v2, s3
	v_readlane_b32 s2, v240, 0
	v_readlane_b32 s3, v240, 1
	s_nop 4
	global_atomic_add v1, v2, s[2:3] offset:1024
